# gla_seq: LDS fragment reads of the two steady-state chunk bodies batched ahead of their MFMAs; XCD-aware role mapping so the 4 dv-slice workgroups of a chain share an L2
# speedup vs baseline: 1.0121x; 1.0015x over previous
; #define LAS __attribute__((address_space(3)))
; __device__ __forceinline__ unsigned xb_add(unsigned* p, unsigned v) { return __hip_atomic_fetch_add(p, v, __ATOMIC_RELAXED, __HIP_MEMORY_SCOPE_AGENT); }
; __device__ __forceinline__ unsigned xb_xcc_id() { return (unsigned)__builtin_amdgcn_s_getreg((3 << 11) | 20) & 0xFu; }
; __device__ __forceinline__ XcdBarrier xcd_barrier_post(unsigned* bar, volatile LAS unsigned* st) {
;     XcdBarrier b; b.bar = bar; b.x = xb_xcc_id(); b.st = st;
;     if (threadIdx.x == 0) (void)xb_add(&bar[XB_XCNT(b.x)], 1u);
;     return b;
; __global__ void __launch_bounds__(512, 2) fwd_megakernel(Params p) {
;     extern __shared__ __attribute__((aligned(16))) unsigned char lds[];
;     cg::grid_group grid = cg::this_grid();
;     LAS unsigned char* ldsl = (LAS unsigned char*)lds;
;     const int lo = p.ph_lo, hi = p.ph_hi;
;     float* xcb = (float*)(p.ws + WS_XC);
;     ...
;     if (threadIdx.x < 2) ((volatile LAS unsigned*)(ldsl + LDS_BYTES - 64))[threadIdx.x] = 0u;
;     __syncthreads();
;     const XcdBarrier xb = xcd_barrier_post((unsigned*)(p.ws + WS_BAR), (volatile LAS unsigned*)(ldsl + LDS_BYTES - 64));
_Z14fwd_megakernel6Params:
	s_mov_b32 s92, s2
	s_mov_b32 s98, 0
	s_mov_b32 s99, 0
	s_mov_b32 s100, 0
	s_mov_b32 s101, 0
	s_load_dwordx8 s[84:91], s[0:1], 0xc0
	s_load_dwordx4 s[80:83], s[0:1], 0xe0
	s_load_dword s2, s[0:1], 0xf0
	s_add_u32 s4, s0, 0xe8
	v_and_b32_e32 v162, 0x3ff, v0
	s_addc_u32 s5, s1, 0
	v_cmp_gt_u32_e32 vcc, 2, v162
	s_waitcnt lgkmcnt(0)
	v_writelane_b32 v241, s2, 0
	s_and_saveexec_b64 s[2:3], vcc
	v_lshl_add_u32 v1, v162, 2, 0
	v_add_u32_e32 v1, 0x23fc0, v1
	v_mov_b32_e32 v2, 0
	ds_write_b32 v1, v2
	s_or_b64 exec, exec, s[2:3]
	s_waitcnt lgkmcnt(0)
	s_barrier
	s_add_u32 s96, s90, 0x88000
	s_getreg_b32 s2, hwreg(HW_REG_XCC_ID, 0, 4)
	s_addc_u32 s97, s91, 0
	s_and_b32 s93, s2, 15
	v_cmp_eq_u32_e64 s[94:95], 0, v162
	s_and_saveexec_b64 s[2:3], s[94:95]
	s_cbranch_execz .LBB0_5
	s_mov_b64 s[6:7], exec
	v_mbcnt_lo_u32_b32 v1, s6, 0
	v_mbcnt_hi_u32_b32 v1, s7, v1
	v_cmp_eq_u32_e32 vcc, 0, v1
	s_and_b64 s[8:9], exec, vcc
	s_mov_b64 exec, s[8:9]
	s_cbranch_execz .LBB0_5
	s_lshl_b32 s8, s93, 8
	s_bcnt1_i32_b64 s6, s[6:7]
	v_mov_b32_e32 v1, s8
	v_mov_b32_e32 v2, s6
	global_atomic_add v1, v2, s[96:97] offset:1024

; #define GSYNC() xcd_barrier(xb)
; __global__ void __launch_bounds__(512, 2) fwd_megakernel(Params p) {
;     ...
;     if (IN(3)) { for (int rep_ = 0; rep_ < NREP(3); ++rep_) { if (rep_) GSYNC(); if (PH(3)) { gla_pre(p, lds); lru_pre(p, lds); GSYNC(); for (int role = blockIdx.x; role < 256; role += gridDim.x) { if (role < 128) gla_seq(p, lds, role); else lru_apply(p, role - 128); }
.LBB0_515:
	s_mov_b32 s45, s99
	s_barrier

; #define GSYNC() xcd_barrier(xb)
; __device__ __forceinline__ void gla_seq(const Params& p, unsigned char* lds, int gb) {
;     ...
;     const int dvs = gb & 3, dir = (gb >> 2) & 1, h = (gb >> 3) & 3, b = gb >> 5;
;     const int chain = (b * 4 + h) * 2 + dir;
; __global__ void __launch_bounds__(512, 2) fwd_megakernel(Params p) {
;     ...
;     if (IN(3)) { for (int rep_ = 0; rep_ < NREP(3); ++rep_) { if (rep_) GSYNC(); if (PH(3)) { gla_pre(p, lds); lru_pre(p, lds); GSYNC(); for (int role = blockIdx.x; role < 256; role += gridDim.x) { if (role < 128) gla_seq(p, lds, role); else lru_apply(p, role - 128); }
.LBB0_521:
	s_and_b64 vcc, exec, s[0:1]
	s_cbranch_vccz .LBB0_516
	s_mov_b32 s99, s45
	s_and_b32 s0, s45, 7
	s_lshr_b32 s2, s45, 3
	s_lshl_b32 s0, s0, 2
	s_lshr_b32 s3, s2, 2
	s_add_i32 s0, s0, s3
	s_lshl_b32 s0, s0, 2
	s_and_b32 s2, s2, 3
	s_or_b32 s45, s0, s2
	s_bfe_u32 s22, s45, 0x20003
	s_lshl_b32 s0, s45, 6
	s_lshl_b32 s50, s22, 8
	s_and_b32 s47, s0, 0xc0
	s_or_b32 s0, s50, s47
	v_add_u32_e32 v0, s0, v106
	v_mul_u32_u24_e32 v0, 0x4400, v0
	s_mov_b32 s6, 0
	s_mov_b64 s[2:3], 0
	v_mov_b32_e32 v1, v135
	s_barrier
	s_branch .LBB0_524

.LBB0_546:
	s_waitcnt lgkmcnt(0)
	s_barrier
	s_add_i32 s26, s47, 4
	s_and_b64 s[2:3], s[2:3], exec
	s_cselect_b32 s2, s47, s26
	s_addk_i32 s33, 0xff80
	s_addk_i32 s46, 0x80
	s_add_i32 s47, s47, 2
	v_lshl_add_u64 v[92:93], v[92:93], 0, s[16:17]
	v_lshl_add_u64 v[94:95], v[94:95], 0, s[14:15]
	s_cmpk_lt_u32 s50, 0x42
	v_lshl_add_u32 v85, s2, 6, v106
	s_mov_b64 s[2:3], 0x400
	v_lshl_add_u64 v[90:91], v[90:91], 0, s[2:3]
	ds_read_b128 v[188:191], v81 offset:61440
	ds_read_b128 v[192:195], v81 offset:61504
	ds_read_b128 v[196:199], v81 offset:61568
	ds_read_b128 v[200:203], v81 offset:61632
	ds_read_b128 v[204:207], v83
	ds_read_b128 v[208:211], v83 offset:64
	ds_read_b128 v[212:215], v148
	ds_read_b128 v[216:219], v148 offset:64
	ds_read_b128 v[220:223], v148 offset:128
	ds_read_b128 v[224:227], v148 offset:192
	ds_read_b128 v[228:231], v149
	ds_read_b128 v[232:235], v149 offset:64
	s_waitcnt lgkmcnt(0)
	v_mfma_f32_16x16x32_bf16 v[96:99], v[188:191], v[212:215], 0
	v_mfma_f32_16x16x32_bf16 v[96:99], v[192:195], v[216:219], v[96:99]
	v_mfma_f32_16x16x32_bf16 v[96:99], v[196:199], v[220:223], v[96:99]
	v_mfma_f32_16x16x32_bf16 v[96:99], v[200:203], v[224:227], v[96:99]
	v_mfma_f32_16x16x32_bf16 v[96:99], v[204:207], v[228:231], v[96:99]
	v_mfma_f32_16x16x32_bf16 v[96:99], v[208:211], v[232:235], v[96:99]
	ds_read_b128 v[212:215], v150
	ds_read_b128 v[216:219], v150 offset:64
	ds_read_b128 v[220:223], v150 offset:128
	ds_read_b128 v[224:227], v150 offset:192
	ds_read_b128 v[228:231], v151
	ds_read_b128 v[232:235], v151 offset:64
	s_waitcnt lgkmcnt(0)
	v_mfma_f32_16x16x32_bf16 v[236:239], v[188:191], v[212:215], 0
	v_mfma_f32_16x16x32_bf16 v[236:239], v[192:195], v[216:219], v[236:239]
	v_mfma_f32_16x16x32_bf16 v[236:239], v[196:199], v[220:223], v[236:239]
	v_mfma_f32_16x16x32_bf16 v[236:239], v[200:203], v[224:227], v[236:239]
	v_mfma_f32_16x16x32_bf16 v[236:239], v[204:207], v[228:231], v[236:239]
	v_mfma_f32_16x16x32_bf16 v[236:239], v[208:211], v[232:235], v[236:239]
	ds_write2_b32 v87, v96, v97 offset0:128 offset1:196
	ds_write2_b32 v139, v98, v99 offset0:8 offset1:76
	ds_read_u16 v192, v142
	ds_read_u16 v188, v142 offset:272
	ds_read_u16 v189, v142 offset:544
	ds_read_u16 v193, v142 offset:816
	ds_read_u16 v190, v142 offset:1088
	ds_read_u16 v194, v142 offset:1360
	ds_read_u16 v191, v142 offset:1632
	ds_read_u16 v195, v142 offset:1904
	ds_read_u16 v200, v142 offset:8704
	ds_read_u16 v196, v142 offset:8976
	ds_read_u16 v197, v142 offset:9248
	ds_read_u16 v201, v142 offset:9520
	ds_read_u16 v198, v142 offset:9792
	ds_read_u16 v202, v142 offset:10064
	ds_read_u16 v199, v142 offset:10336
	ds_read_u16 v203, v142 offset:10608
	ds_read_b128 v[204:207], v136
	ds_read_b128 v[208:211], v137
	ds_read_b128 v[212:215], v137 offset:2304
	ds_read_b128 v[216:219], v137 offset:4608
	ds_read_b128 v[220:223], v136 offset:64
	ds_read_b128 v[224:227], v137 offset:64
	ds_read_b128 v[228:231], v137 offset:2368
	ds_read_b128 v[232:235], v137 offset:4672
	s_waitcnt lgkmcnt(8)
	v_perm_b32 v189, v193, v189, s44
	v_perm_b32 v188, v188, v192, s44
	v_perm_b32 v190, v194, v190, s44
	v_perm_b32 v191, v195, v191, s44
	v_perm_b32 v197, v201, v197, s44
	v_perm_b32 v196, v196, v200, s44
	v_perm_b32 v198, v202, v198, s44
	v_perm_b32 v199, v203, v199, s44
	ds_write2_b32 v140, v236, v237 offset0:128 offset1:196
	ds_write2_b32 v141, v238, v239 offset0:8 offset1:76
	s_waitcnt lgkmcnt(6)
	s_waitcnt lgkmcnt(2)
	v_mfma_f32_16x16x32_bf16 v[48:51], v[188:191], v[204:207], v[48:51]
	v_mfma_f32_16x16x32_bf16 v[52:55], v[188:191], v[208:211], v[52:55]
	v_mfma_f32_16x16x32_bf16 v[56:59], v[188:191], v[212:215], v[56:59]
	v_mfma_f32_16x16x32_bf16 v[60:63], v[188:191], v[216:219], v[60:63]
	v_mfma_f32_16x16x32_bf16 v[48:51], v[196:199], v[220:223], v[48:51]
	v_mfma_f32_16x16x32_bf16 v[52:55], v[196:199], v[224:227], v[52:55]
	v_mfma_f32_16x16x32_bf16 v[56:59], v[196:199], v[228:231], v[56:59]
	v_mfma_f32_16x16x32_bf16 v[60:63], v[196:199], v[232:235], v[60:63]
	ds_read_b128 v[96:99], v65 offset:60928
	s_waitcnt lgkmcnt(0)
	s_barrier
	v_pk_mul_f32 v[50:51], v[50:51], v[98:99]
	v_pk_mul_f32 v[48:49], v[48:49], v[96:97]
	v_pk_mul_f32 v[54:55], v[54:55], v[98:99]
	v_pk_mul_f32 v[52:53], v[52:53], v[96:97]
	v_pk_mul_f32 v[56:57], v[56:57], v[96:97]
	v_pk_mul_f32 v[60:61], v[60:61], v[96:97]
	v_cvt_pk_bf16_f32 v96, v48, v49
	v_cvt_pk_bf16_f32 v97, v50, v51
	v_pk_mul_f32 v[58:59], v[58:59], v[98:99]
	ds_write_b64 v143, v[96:97]
	v_cvt_pk_bf16_f32 v96, v52, v53
	v_cvt_pk_bf16_f32 v97, v54, v55
	v_pk_mul_f32 v[62:63], v[62:63], v[98:99]
	ds_write_b64 v145, v[96:97]
	v_cvt_pk_bf16_f32 v96, v56, v57
	v_cvt_pk_bf16_f32 v97, v58, v59
	ds_write_b64 v146, v[96:97]
	v_cvt_pk_bf16_f32 v96, v60, v61
	v_cvt_pk_bf16_f32 v97, v62, v63
	ds_write_b64 v145, v[96:97] offset:8704
	v_sub_u32_e32 v96, s51, v85
	v_cndmask_b32_e64 v96, v96, v85, s[6:7]
	v_ashrrev_i32_e32 v97, 31, v96
	v_lshl_add_u64 v[96:97], s[24:25], 0, v[96:97]
	v_lshlrev_b64 v[96:97], 11, v[96:97]
	v_lshl_add_u64 v[156:157], v[76:77], 0, v[96:97]
	ds_read_b128 v[96:99], v130 offset:25088
	ds_read_b128 v[152:155], v130 offset:25104
	s_waitcnt lgkmcnt(1)
	v_cvt_pk_bf16_f32 v96, v96, v97
	v_cvt_pk_bf16_f32 v97, v98, v99
	s_waitcnt lgkmcnt(0)
	v_cvt_pk_bf16_f32 v98, v152, v153
	v_cvt_pk_bf16_f32 v99, v154, v155
	global_store_dwordx4 v[156:157], v[96:99], off
	s_cbranch_scc0 .LBB0_515

.LBB0_555:
	s_waitcnt lgkmcnt(0)
	s_barrier
	s_cmp_gt_u32 s50, 3
	s_cselect_b64 s[2:3], -1, 0
	s_add_i32 s26, s46, 0xffffff00
	s_and_b64 s[24:25], s[2:3], exec
	s_cselect_b32 s24, s26, s46
	s_cselect_b32 s25, s1, s23
	s_mov_b64 s[26:27], -1
	v_or_b32_e32 v85, s24, v106
	s_movk_i32 s24, 0xfff
	s_cselect_b32 s51, s24, 0xff
	s_cselect_b32 s24, s0, s22
	s_and_b64 vcc, exec, s[20:21]
	ds_read_b128 v[188:191], v81 offset:61440
	ds_read_b128 v[192:195], v81 offset:61504
	ds_read_b128 v[196:199], v81 offset:61568
	ds_read_b128 v[200:203], v81 offset:61632
	ds_read_b128 v[204:207], v83
	ds_read_b128 v[208:211], v83 offset:64
	ds_read_b128 v[212:215], v148
	ds_read_b128 v[216:219], v148 offset:64
	ds_read_b128 v[220:223], v148 offset:128
	ds_read_b128 v[224:227], v148 offset:192
	ds_read_b128 v[228:231], v149
	ds_read_b128 v[232:235], v149 offset:64
	s_waitcnt lgkmcnt(0)
	v_mfma_f32_16x16x32_bf16 v[152:155], v[188:191], v[212:215], 0
	v_mfma_f32_16x16x32_bf16 v[152:155], v[192:195], v[216:219], v[152:155]
	v_mfma_f32_16x16x32_bf16 v[152:155], v[196:199], v[220:223], v[152:155]
	v_mfma_f32_16x16x32_bf16 v[152:155], v[200:203], v[224:227], v[152:155]
	v_mfma_f32_16x16x32_bf16 v[152:155], v[204:207], v[228:231], v[152:155]
	v_mfma_f32_16x16x32_bf16 v[152:155], v[208:211], v[232:235], v[152:155]
	ds_read_b128 v[212:215], v150
	ds_read_b128 v[216:219], v150 offset:64
	ds_read_b128 v[220:223], v150 offset:128
	ds_read_b128 v[224:227], v150 offset:192
	ds_read_b128 v[228:231], v151
	ds_read_b128 v[232:235], v151 offset:64
	s_waitcnt lgkmcnt(0)
	v_mfma_f32_16x16x32_bf16 v[236:239], v[188:191], v[212:215], 0
	v_mfma_f32_16x16x32_bf16 v[236:239], v[192:195], v[216:219], v[236:239]
	v_mfma_f32_16x16x32_bf16 v[236:239], v[196:199], v[220:223], v[236:239]
	v_mfma_f32_16x16x32_bf16 v[236:239], v[200:203], v[224:227], v[236:239]
	v_mfma_f32_16x16x32_bf16 v[236:239], v[204:207], v[228:231], v[236:239]
	v_mfma_f32_16x16x32_bf16 v[236:239], v[208:211], v[232:235], v[236:239]
	ds_write2_b32 v87, v152, v153 offset0:128 offset1:196
	ds_write2_b32 v139, v154, v155 offset0:8 offset1:76
	ds_read_u16 v192, v142
	ds_read_u16 v188, v142 offset:272
	ds_read_u16 v189, v142 offset:544
	ds_read_u16 v193, v142 offset:816
	ds_read_u16 v190, v142 offset:1088
	ds_read_u16 v194, v142 offset:1360
	ds_read_u16 v191, v142 offset:1632
	ds_read_u16 v195, v142 offset:1904
	ds_read_u16 v200, v142 offset:8704
	ds_read_u16 v196, v142 offset:8976
	ds_read_u16 v197, v142 offset:9248
	ds_read_u16 v201, v142 offset:9520
	ds_read_u16 v198, v142 offset:9792
	ds_read_u16 v202, v142 offset:10064
	ds_read_u16 v199, v142 offset:10336
	ds_read_u16 v203, v142 offset:10608
	ds_read_b128 v[204:207], v136
	ds_read_b128 v[208:211], v137
	ds_read_b128 v[212:215], v137 offset:2304
	ds_read_b128 v[216:219], v137 offset:4608
	ds_read_b128 v[220:223], v136 offset:64
	ds_read_b128 v[224:227], v137 offset:64
	ds_read_b128 v[228:231], v137 offset:2368
	ds_read_b128 v[232:235], v137 offset:4672
	s_waitcnt lgkmcnt(8)
	v_perm_b32 v189, v193, v189, s44
	v_perm_b32 v188, v188, v192, s44
	v_perm_b32 v190, v194, v190, s44
	v_perm_b32 v191, v195, v191, s44
	v_perm_b32 v197, v201, v197, s44
	v_perm_b32 v196, v196, v200, s44
	v_perm_b32 v198, v202, v198, s44
	v_perm_b32 v199, v203, v199, s44
	ds_write2_b32 v140, v236, v237 offset0:128 offset1:196
	ds_write2_b32 v141, v238, v239 offset0:8 offset1:76
	s_waitcnt lgkmcnt(6)
	s_waitcnt lgkmcnt(2)
	v_mfma_f32_16x16x32_bf16 v[48:51], v[188:191], v[204:207], v[48:51]
	v_mfma_f32_16x16x32_bf16 v[52:55], v[188:191], v[208:211], v[52:55]
	v_mfma_f32_16x16x32_bf16 v[56:59], v[188:191], v[212:215], v[56:59]
	v_mfma_f32_16x16x32_bf16 v[60:63], v[188:191], v[216:219], v[60:63]
	v_mfma_f32_16x16x32_bf16 v[48:51], v[196:199], v[220:223], v[48:51]
	v_mfma_f32_16x16x32_bf16 v[52:55], v[196:199], v[224:227], v[52:55]
	v_mfma_f32_16x16x32_bf16 v[56:59], v[196:199], v[228:231], v[56:59]
	v_mfma_f32_16x16x32_bf16 v[60:63], v[196:199], v[232:235], v[60:63]
	ds_read_b128 v[152:155], v65 offset:60928
	s_waitcnt lgkmcnt(0)
	s_barrier
	v_pk_mul_f32 v[50:51], v[50:51], v[154:155]
	v_pk_mul_f32 v[48:49], v[48:49], v[152:153]
	v_pk_mul_f32 v[54:55], v[54:55], v[154:155]
	v_pk_mul_f32 v[52:53], v[52:53], v[152:153]
	v_pk_mul_f32 v[56:57], v[56:57], v[152:153]
	v_pk_mul_f32 v[60:61], v[60:61], v[152:153]
	v_cvt_pk_bf16_f32 v152, v48, v49
	v_cvt_pk_bf16_f32 v153, v50, v51
	v_pk_mul_f32 v[58:59], v[58:59], v[154:155]
	ds_write_b64 v143, v[152:153]
	v_cvt_pk_bf16_f32 v152, v52, v53
	v_cvt_pk_bf16_f32 v153, v54, v55
	v_pk_mul_f32 v[62:63], v[62:63], v[154:155]
	ds_write_b64 v145, v[152:153]
	v_cvt_pk_bf16_f32 v152, v56, v57
	v_cvt_pk_bf16_f32 v153, v58, v59
	ds_write_b64 v146, v[152:153]
	v_cvt_pk_bf16_f32 v152, v60, v61
	v_cvt_pk_bf16_f32 v153, v62, v63
	ds_write_b64 v145, v[152:153] offset:8704
	v_sub_u32_e32 v152, s51, v85
	v_cndmask_b32_e64 v152, v152, v85, s[6:7]
	v_ashrrev_i32_e32 v153, 31, v152
	v_lshl_add_u64 v[152:153], s[24:25], 0, v[152:153]
	v_lshlrev_b64 v[152:153], 11, v[152:153]
	v_lshl_add_u64 v[164:165], v[76:77], 0, v[152:153]
	ds_read_b128 v[152:155], v130 offset:25088
	ds_read_b128 v[156:159], v130 offset:25104
	s_waitcnt lgkmcnt(1)
	v_cvt_pk_bf16_f32 v152, v152, v153
	v_cvt_pk_bf16_f32 v153, v154, v155
	s_waitcnt lgkmcnt(0)
	v_cvt_pk_bf16_f32 v154, v156, v157
	v_cvt_pk_bf16_f32 v155, v158, v159
	global_store_dwordx4 v[164:165], v[152:155], off
	s_waitcnt vmcnt(7)
	ds_write_b128 v113, v[24:27] offset:61440
	s_waitcnt vmcnt(5)
	ds_write_b128 v113, v[32:35] offset:61456
	ds_write_b128 v114, v[28:31]
	s_waitcnt vmcnt(4)
	ds_write_b128 v114, v[36:39] offset:16
	s_waitcnt vmcnt(3)
	ds_write_b128 v118, v[40:43]
	s_cbranch_vccnz .LBB0_561
	s_andn2_b64 vcc, exec, s[26:27]
	s_cbranch_vccz .LBB0_562

; __global__ void __launch_bounds__(512, 2) fwd_megakernel(Params p) {
	.amdhsa_kernel _Z14fwd_megakernel6Params
		.amdhsa_group_segment_fixed_size 0
		.amdhsa_private_segment_fixed_size 0
		.amdhsa_kernarg_size 488
		.amdhsa_user_sgpr_count 2
		.amdhsa_user_sgpr_dispatch_ptr 0
		.amdhsa_user_sgpr_queue_ptr 0
		.amdhsa_user_sgpr_kernarg_segment_ptr 1
		.amdhsa_user_sgpr_dispatch_id 0
		.amdhsa_user_sgpr_kernarg_preload_length 0
		.amdhsa_user_sgpr_kernarg_preload_offset 0
		.amdhsa_user_sgpr_private_segment_size 0
		.amdhsa_uses_dynamic_stack 0
		.amdhsa_enable_private_segment 0
		.amdhsa_system_sgpr_workgroup_id_x 1
		.amdhsa_system_sgpr_workgroup_id_y 0
		.amdhsa_system_sgpr_workgroup_id_z 0
		.amdhsa_system_sgpr_workgroup_info 0
		.amdhsa_system_vgpr_workitem_id 2
		.amdhsa_next_free_vgpr 242
		.amdhsa_next_free_sgpr 102
		.amdhsa_accum_offset 244
		.amdhsa_reserve_vcc 1
		.amdhsa_float_round_mode_32 0
		.amdhsa_float_round_mode_16_64 0
		.amdhsa_float_denorm_mode_32 3
		.amdhsa_float_denorm_mode_16_64 3
		.amdhsa_dx10_clamp 1
		.amdhsa_ieee_mode 1
		.amdhsa_fp16_overflow 0
		.amdhsa_tg_split 0
		.amdhsa_exception_fp_ieee_invalid_op 0
		.amdhsa_exception_fp_denorm_src 0
		.amdhsa_exception_fp_ieee_div_zero 0
		.amdhsa_exception_fp_ieee_overflow 0
		.amdhsa_exception_fp_ieee_underflow 0
		.amdhsa_exception_fp_ieee_inexact 0
		.amdhsa_exception_int_div_zero 0
	.end_amdhsa_kernel

; __global__ void __launch_bounds__(512, 2) fwd_megakernel(Params p) {
amdhsa.kernels:
  - .agpr_count:     0
    .args:
      - .offset:         0
        .size:           232
        .value_kind:     by_value
      - .offset:         232
        .size:           4
        .value_kind:     hidden_block_count_x
      - .offset:         236
        .size:           4
        .value_kind:     hidden_block_count_y
      - .offset:         240
        .size:           4
        .value_kind:     hidden_block_count_z
      - .offset:         244
        .size:           2
        .value_kind:     hidden_group_size_x
      - .offset:         246
        .size:           2
        .value_kind:     hidden_group_size_y
      - .offset:         248
        .size:           2
        .value_kind:     hidden_group_size_z
      - .offset:         250
        .size:           2
        .value_kind:     hidden_remainder_x
      - .offset:         252
        .size:           2
        .value_kind:     hidden_remainder_y
      - .offset:         254
        .size:           2
        .value_kind:     hidden_remainder_z
      - .offset:         272
        .size:           8
        .value_kind:     hidden_global_offset_x
      - .offset:         280
        .size:           8
        .value_kind:     hidden_global_offset_y
      - .offset:         288
        .size:           8
        .value_kind:     hidden_global_offset_z
      - .offset:         296
        .size:           2
        .value_kind:     hidden_grid_dims
      - .offset:         320
        .size:           8
        .value_kind:     hidden_multigrid_sync_arg
      - .offset:         352
        .size:           4
        .value_kind:     hidden_dynamic_lds_size
    .group_segment_fixed_size: 0
    .kernarg_segment_align: 8
    .kernarg_segment_size: 488
    .language:       OpenCL C
    .language_version:
      - 2
      - 0
    .max_flat_workgroup_size: 512
    .name:           _Z14fwd_megakernel6Params
    .private_segment_fixed_size: 0
    .sgpr_count:     108
    .sgpr_spill_count: 78
    .symbol:         _Z14fwd_megakernel6Params.kd
    .uniform_work_group_size: 1
    .uses_dynamic_stack: false
    .vgpr_count:     242
    .vgpr_spill_count: 0
    .wavefront_size: 64
